# MIX work queue: early pop atomic plus ds_write/ds_read instead of flat LDS accesses for the queue index (on top of vt_pair2)
# baseline (speedup 1.0000x reference)
; template <int DQK, int DV, bool CAUSAL, bool MLA> ...
;     ...
;     const int tid_ = mk_tid(wid_s);
;     const int tid = tid_, lane = tid & 63, wv = tid >> 6, g = lane >> 4, j = lane & 15;
;     const int qrow = q0 + wv * 16 + j;
;     bf16x8 qf[NKS];
;     {
;         float qv[NKS][8]; float ss = 0.f;
; #pragma unroll
;         for (int ks = 0; ks < NKS; ++ks) { const u32x4 w = *(const GAS u32x4*)(Qb + (size_t)qrow * ldq + 32 * ks + 8 * g);
;             qv[ks][0] = bflo(w.x); qv[ks][1] = bfhi(w.x); qv[ks][2] = bflo(w.y); qv[ks][3] = bfhi(w.y); qv[ks][4] = bflo(w.z); qv[ks][5] = bfhi(w.z); qv[ks][6] = bflo(w.w); qv[ks][7] = bfhi(w.w);
; #pragma unroll
;             for (int e = 0; e < 8; ++e) ss += qv[ks][e] * qv[ks][e]; }
;         ss += __shfl_xor(ss, 16); ss += __shfl_xor(ss, 32);
;         const float rs = rsqrtf(ss * (1.f / DQK) + 1e-6f);
; #pragma unroll
;         for (int ks = 0; ks < NKS; ++ks)
; #pragma unroll
;             for (int e = 0; e < 8; ++e) qv[ks][e] *= rs * qgain[32 * ks + 8 * g + e];
;         if (MLA) {
;             const int ps = pos[qrow];
; #pragma unroll
;             for (int e = 0; e < 8; ++e) { const float mine = qv[2][e], other = __shfl_xor(mine, 32); float c, s; rope_cs(ps, 8 * (g & 1) + e, c, s);
;                 qv[2][e] = (g < 2) ? (mine * c - other * s) : (mine * c + other * s); }
;         }
; #pragma unroll
;         for (int ks = 0; ks < NKS; ++ks) { u32x4 w; w.x = pk2(qv[ks][0] * qscale, qv[ks][1] * qscale); w.y = pk2(qv[ks][2] * qscale, qv[ks][3] * qscale);
;             w.z = pk2(qv[ks][4] * qscale, qv[ks][5] * qscale); w.w = pk2(qv[ks][6] * qscale, qv[ks][7] * qscale); qf[ks] = __builtin_bit_cast(bf16x8, w); }
;     }
;     f32x4 oT[NDT];
; #pragma unroll
;     for (int d = 0; d < NDT; ++d) oT[d] = (f32x4){0.f, 0.f, 0.f, 0.f};
; __global__ void __launch_bounds__(512, 2) fwd_kernel(Params parg) {
;     ...
;                 unsigned* ctr = ctl + q * 4 + l * 2 + r; volatile int* qidx = (volatile int*)(lds + QIDX_OFF);
;                 for (;;) {
;                     __syncthreads();
;                     if (mk_tid(wid_s) == 0) *qidx = (int)atomicAdd(ctr, 1u);
;                     __syncthreads();
;                     const int u = *qidx;
;                     if (u >= 512 || !ON(5) || (q && RB(12))) break;
;                     const int qb = 15 - (u >> 5), bh = u & 31, bl = bh >> 3, h = bh & 7;
.LBB0_1420:
	v_cmp_eq_u32_e32 vcc, 0, v169
	s_and_saveexec_b64 s[2:3], vcc
	v_mov_b64_e32 v[0:1], s[6:7]
	flat_atomic_add v2, v[0:1], v170 sc0
	s_mov_b64 exec, s[2:3]
	s_waitcnt vmcnt(0)
	v_mov_b32_e32 v0, v169
	s_waitcnt lgkmcnt(0)
	s_barrier
	s_nop 0
	v_cmp_eq_u32_e32 vcc, 0, v0
	s_and_saveexec_b64 s[2:3], vcc
	s_cbranch_execz .LBB0_1422
	s_add_i32 s0, 0, 0x222e0
	s_mov_b64 s[4:5], src_shared_base
	s_cmp_lg_u32 s0, -1
	s_cselect_b32 s0, s0, 0
	s_cselect_b32 s4, s5, 0
	v_mov_b32_e32 v0, s0
	v_mov_b32_e32 v1, s4
	s_waitcnt vmcnt(0) lgkmcnt(0)
	ds_write_b32 v0, v2
.LBB0_1422:
	s_or_b64 exec, exec, s[2:3]
	s_add_i32 s0, 0, 0x222e0
	s_mov_b64 s[2:3], src_shared_base
	s_cmp_lg_u32 s0, -1
	s_cselect_b32 s0, s0, 0
	s_cselect_b32 s2, s3, 0
	v_mov_b32_e32 v0, s0
	v_mov_b32_e32 v1, s2
	s_waitcnt lgkmcnt(0)
	s_barrier
	ds_read_b32 v64, v0
	s_mov_b64 s[2:3], -1
	s_waitcnt lgkmcnt(0)
	v_cmp_gt_i32_e32 vcc, s51, v64
	s_and_saveexec_b64 s[10:11], vcc
	s_cbranch_execz .LBB0_1419
	v_bfe_u32 v7, v64, 3, 2
	v_readlane_b32 s12, v254, 2
	v_and_b32_e32 v70, 7, v64
	v_readlane_b32 s14, v254, 4
	v_readlane_b32 s15, v254, 5
	v_mul_u32_u24_e32 v0, 0x180000, v7
	s_mov_b64 s[2:3], s[14:15]
	v_lshlrev_b32_e32 v144, 1, v0
	v_mul_u32_u24_e32 v2, 0x60, v70
	v_lshlrev_b32_e32 v2, 1, v2
	v_lshl_add_u64 v[0:1], s[2:3], 0, v[144:145]
	v_mov_b32_e32 v3, v145
	v_lshl_add_u64 v[0:1], v[0:1], 0, v[2:3]
	s_mov_b64 s[2:3], 0xde00000
	v_readlane_b32 s13, v254, 3
	v_lshl_add_u64 v[0:1], v[0:1], 0, s[2:3]
	s_mov_b64 s[2:3], s[14:15]
	s_mov_b64 s[12:13], s[14:15]
	v_lshl_add_u64 v[4:5], s[2:3], 0, v[144:145]
	v_readlane_b32 s14, v254, 0
	v_lshl_add_u64 v[2:3], v[4:5], 0, v[2:3]
	s_mov_b64 s[2:3], 0xea00000
	v_readlane_b32 s15, v254, 1
	v_lshl_add_u64 v[40:41], v[2:3], 0, s[2:3]
	s_load_dwordx2 s[2:3], s[14:15], 0xf8
	v_readlane_b32 s4, v254, 58
	v_readlane_b32 s5, v254, 59
	s_lshl_b64 s[4:5], s[4:5], 2
	v_mov_b32_e32 v75, v169
	s_waitcnt lgkmcnt(0)
	s_add_u32 s2, s2, s4
	s_addc_u32 s3, s3, s5
	s_load_dwordx2 s[4:5], s[14:15], 0x10
	v_ashrrev_i32_e32 v73, 5, v64
	v_sub_u32_e32 v6, 15, v73
	v_ashrrev_i32_e32 v4, 2, v75
	v_or_b32_e32 v71, s57, v7
	v_and_b32_e32 v4, -16, v4
	v_lshlrev_b32_e32 v2, 11, v71
	v_and_b32_e32 v74, 15, v75
	v_lshl_add_u32 v72, v6, 7, v4
	v_ashrrev_i32_e32 v3, 31, v2
	v_bfe_u32 v76, v75, 4, 2
	v_or_b32_e32 v56, v72, v74
	s_waitcnt lgkmcnt(0)
	v_lshl_add_u64 v[2:3], v[2:3], 2, s[4:5]
	v_mad_i64_i32 v[0:1], s[4:5], v56, s93, v[0:1]
	v_lshlrev_b32_e32 v144, 4, v76
	v_lshl_add_u64 v[0:1], v[0:1], 0, v[144:145]
	global_load_dwordx4 v[24:27], v[0:1], off
	global_load_dwordx4 v[16:19], v[0:1], off offset:64
	global_load_dwordx4 v[8:11], v[0:1], off offset:128
	v_ashrrev_i32_e32 v57, 31, v56
	v_lshlrev_b32_e32 v20, 5, v76
	v_lshl_add_u64 v[0:1], v[56:57], 2, v[2:3]
	global_load_dword v57, v[0:1], off
	s_nop 0
	global_load_dwordx4 v[0:3], v20, s[2:3] offset:272
	global_load_dwordx4 v[4:7], v20, s[2:3] offset:256
	s_mov_b32 s0, 0x800000
	s_waitcnt vmcnt(5)
	v_lshlrev_b32_e32 v46, 16, v24
	s_waitcnt vmcnt(4)
	v_lshlrev_b32_e32 v28, 16, v19
	s_waitcnt vmcnt(3)
	v_lshlrev_b32_e32 v48, 16, v11
	v_and_b32_e32 v49, 0xffff0000, v11
	v_lshlrev_b32_e32 v44, 16, v10
	v_and_b32_e32 v45, 0xffff0000, v10
	v_lshlrev_b32_e32 v42, 16, v9
	v_and_b32_e32 v43, 0xffff0000, v9
	v_lshlrev_b32_e32 v50, 16, v8
	v_and_b32_e32 v51, 0xffff0000, v8
	v_and_b32_e32 v29, 0xffff0000, v19
	global_load_dwordx4 v[8:11], v20, s[2:3] offset:144
	global_load_dwordx4 v[12:15], v20, s[2:3] offset:128
	v_lshlrev_b32_e32 v30, 16, v18
	v_and_b32_e32 v31, 0xffff0000, v18
	v_lshlrev_b32_e32 v32, 16, v17
	v_and_b32_e32 v33, 0xffff0000, v17
	v_lshlrev_b32_e32 v34, 16, v16
	v_and_b32_e32 v35, 0xffff0000, v16
	global_load_dwordx4 v[16:19], v20, s[2:3] offset:16
	s_nop 0
	global_load_dwordx4 v[20:23], v20, s[2:3]
	v_and_b32_e32 v47, 0xffff0000, v24
	v_lshlrev_b32_e32 v36, 16, v27
	v_and_b32_e32 v37, 0xffff0000, v27
	v_lshlrev_b32_e32 v38, 16, v26
	v_and_b32_e32 v39, 0xffff0000, v26
	v_lshlrev_b32_e32 v26, 16, v25
	v_and_b32_e32 v27, 0xffff0000, v25
	v_pk_mul_f32 v[24:25], v[46:47], v[46:47]
	v_pk_mul_f32 v[84:85], v[26:27], v[26:27]
	v_add_f32_e32 v24, v24, v25
	v_add_f32_e32 v24, v84, v24
	v_pk_mul_f32 v[82:83], v[38:39], v[38:39]
	v_add_f32_e32 v24, v85, v24
	v_add_f32_e32 v24, v82, v24
	v_pk_mul_f32 v[80:81], v[36:37], v[36:37]
	v_add_f32_e32 v24, v83, v24
	v_add_f32_e32 v24, v80, v24
	v_pk_mul_f32 v[78:79], v[34:35], v[34:35]
	v_add_f32_e32 v24, v81, v24
	v_add_f32_e32 v24, v78, v24
	v_pk_mul_f32 v[68:69], v[32:33], v[32:33]
	v_add_f32_e32 v24, v79, v24
	v_add_f32_e32 v24, v68, v24
	v_pk_mul_f32 v[66:67], v[30:31], v[30:31]
	v_add_f32_e32 v24, v69, v24
	v_add_f32_e32 v24, v66, v24
	v_pk_mul_f32 v[62:63], v[28:29], v[28:29]
	v_add_f32_e32 v24, v67, v24
	v_add_f32_e32 v24, v62, v24
	v_pk_mul_f32 v[60:61], v[50:51], v[50:51]
	v_add_f32_e32 v24, v63, v24
	v_add_f32_e32 v24, v60, v24
	v_pk_mul_f32 v[58:59], v[42:43], v[42:43]
	v_add_f32_e32 v24, v61, v24
	v_add_f32_e32 v24, v58, v24
	v_pk_mul_f32 v[54:55], v[44:45], v[44:45]
	v_add_f32_e32 v24, v59, v24
	v_add_f32_e32 v24, v54, v24
	v_pk_mul_f32 v[52:53], v[48:49], v[48:49]
	v_add_f32_e32 v24, v55, v24
	v_add_f32_e32 v24, v52, v24
	v_add_f32_e32 v24, v53, v24
	ds_bpermute_b32 v25, v138, v24
	s_waitcnt lgkmcnt(0)
	v_add_f32_e32 v24, v24, v25
	ds_bpermute_b32 v25, v139, v24
	s_waitcnt lgkmcnt(0)
	v_add_f32_e32 v24, v24, v25
	v_fmamk_f32 v24, v24, 0x3c2aaaab, v171
	v_cmp_gt_f32_e32 vcc, s0, v24
	v_mul_f32_e32 v25, 0x4b800000, v24
	s_mov_b32 s0, 0x2aaaaaab
	v_cndmask_b32_e32 v24, v24, v25, vcc
	v_rsq_f32_e32 v24, v24
	s_nop 0
	v_mul_f32_e32 v25, 0x45800000, v24
	v_cndmask_b32_e32 v62, v24, v25, vcc
	s_waitcnt vmcnt(4)
	v_pk_mul_f32 v[4:5], v[4:5], v[62:63] op_sel_hi:[1,0]
	v_pk_mul_f32 v[0:1], v[0:1], v[62:63] op_sel_hi:[1,0]
	v_pk_mul_f32 v[24:25], v[4:5], v[50:51]
	v_pk_mul_f32 v[4:5], v[6:7], v[62:63] op_sel_hi:[1,0]
	v_pk_mul_f32 v[44:45], v[0:1], v[44:45]
	v_pk_mul_f32 v[0:1], v[2:3], v[62:63] op_sel_hi:[1,0]
	v_pk_mul_f32 v[42:43], v[4:5], v[42:43]
	v_pk_mul_f32 v[48:49], v[0:1], v[48:49]
	ds_bpermute_b32 v60, v139, v24
	ds_bpermute_b32 v61, v139, v25
	ds_bpermute_b32 v58, v139, v42
	ds_bpermute_b32 v59, v139, v43
	ds_bpermute_b32 v52, v139, v44
	ds_bpermute_b32 v53, v139, v45
	ds_bpermute_b32 v50, v139, v48
	ds_bpermute_b32 v51, v139, v49
	v_mul_hi_i32 v0, v75, s0
	v_cmp_gt_i32_e32 vcc, s33, v75
	v_lshrrev_b32_e32 v77, 31, v0
	v_ashrrev_i32_e32 v78, 1, v0
	s_and_saveexec_b64 s[2:3], vcc
	s_cbranch_execz .LBB0_1425
	v_add_u32_e32 v0, v78, v77
	v_mul_lo_u32 v1, v0, 12
	v_sub_u32_e32 v2, v75, v1
	v_lshlrev_b32_e32 v2, 3, v2
	v_mad_i64_i32 v[0:1], s[4:5], v0, s93, v[40:41]
	v_ashrrev_i32_e32 v3, 31, v2
	v_lshl_add_u64 v[0:1], v[2:3], 1, v[0:1]
	global_load_dwordx4 v[0:3], v[0:1], off
